# v100 + fused final-LN epilogue pass-1 loads also paired per 128B line (row-major halves)
# speedup vs baseline: 1.0072x; 1.0072x over previous
.Lepi_A_final:
	s_mov_b64 s[40:41], 0
	v_lshl_add_u32 v248, s58, 8, v158
	v_lshl_or_b32 v249, s2, 8, v159
	v_lshlrev_b32_e32 v248, 3, v248
	v_lshlrev_b32_e32 v249, 2, v249
	s_mov_b32 s4, s58
	s_mov_b32 s5, s2
	s_ashr_i32 s59, s58, 31
	s_lshl_b64 s[28:29], s[58:59], 20
	s_add_u32 s60, s73, s28
	s_addc_u32 s61, s72, s29
	v_readlane_b32 s16, v252, 12
	v_readlane_b32 s17, v252, 13
	s_nop 3
	s_add_u32 s58, s16, s28
	s_addc_u32 s59, s17, s29
	v_mov_b32_e32 v214, 0
	v_mov_b32_e32 v215, 0
	v_mov_b32_e32 v216, 0
	v_mov_b32_e32 v217, 0
	v_mov_b32_e32 v218, 0
	v_mov_b32_e32 v219, 0
	v_mov_b32_e32 v220, 0
	v_mov_b32_e32 v221, 0
	v_mov_b32_e32 v232, 0
	v_mov_b32_e32 v233, 0
	v_mov_b32_e32 v234, 0
	v_mov_b32_e32 v235, 0
	v_mov_b32_e32 v236, 0
	v_mov_b32_e32 v237, 0
	v_mov_b32_e32 v238, 0
	v_mov_b32_e32 v239, 0
	global_load_dwordx2 v[112:113], v248, s[92:93]
	global_load_dwordx2 v[200:201], v248, s[92:93] offset:128
	global_load_dwordx2 v[202:203], v248, s[92:93] offset:256
	global_load_dwordx2 v[204:205], v248, s[92:93] offset:384
	global_load_dwordx2 v[206:207], v248, s[92:93] offset:1024
	global_load_dwordx2 v[208:209], v248, s[92:93] offset:1152
	global_load_dwordx2 v[210:211], v248, s[92:93] offset:1280
	global_load_dwordx2 v[212:213], v248, s[92:93] offset:1408
	global_load_dwordx4 v[184:187], v249, s[48:49]
	global_load_dwordx4 v[188:191], v249, s[84:85]
	v_lshl_add_u32 v240, v160, 2, v249
	v_lshl_add_u32 v241, v164, 2, v249
	v_lshl_add_u32 v242, v166, 2, v249
	v_lshl_add_u32 v243, v168, 2, v249
	v_lshl_add_u32 v244, v162, 2, v249
	v_lshl_add_u32 v245, v170, 2, v249
	v_lshl_add_u32 v246, v172, 2, v249
	v_lshl_add_u32 v247, v174, 2, v249
	global_load_dwordx4 v[192:195], v249, s[48:49] offset:64
	global_load_dwordx4 v[196:199], v249, s[84:85] offset:64
	global_load_dwordx4 v[108:111], v240, s[60:61]
	global_load_dwordx4 v[130:133], v240, s[60:61] offset:64
	global_load_dwordx4 v[134:137], v241, s[60:61]
	global_load_dwordx4 v[180:183], v241, s[60:61] offset:64
	s_waitcnt vmcnt(3)
	v_pk_add_f32 v[108:109], v[108:109], v[112:113] op_sel_hi:[1,0] neg_lo:[0,1] neg_hi:[0,1]
	v_pk_add_f32 v[110:111], v[110:111], v[112:113] op_sel_hi:[1,0] neg_lo:[0,1] neg_hi:[0,1]
	v_pk_mul_f32 v[108:109], v[108:109], v[112:113] op_sel:[0,1] op_sel_hi:[1,1]
	v_pk_mul_f32 v[110:111], v[110:111], v[112:113] op_sel:[0,1] op_sel_hi:[1,1]
	v_pk_fma_f32 v[108:109], v[184:185], v[108:109], v[188:189]
	v_pk_fma_f32 v[110:111], v[186:187], v[110:111], v[190:191]
	v_pk_mul_f32 v[108:109], v[108:109], s[82:83] op_sel_hi:[1,0]
	v_pk_mul_f32 v[110:111], v[110:111], s[82:83] op_sel_hi:[1,0]
	v_pk_fma_f32 v[138:139], v[138:139], 0.5, v[108:109] op_sel_hi:[1,0,1]
	v_pk_fma_f32 v[140:141], v[140:141], 0.5, v[110:111] op_sel_hi:[1,0,1]
	global_load_dwordx4 v[108:111], v242, s[60:61]
	v_add_f32_e32 v214, v214, v138
	v_add_f32_e32 v214, v214, v139
	v_add_f32_e32 v214, v214, v140
	v_add_f32_e32 v214, v214, v141
	v_fmac_f32_e32 v215, v138, v138
	v_fmac_f32_e32 v215, v139, v139
	v_fmac_f32_e32 v215, v140, v140
	v_fmac_f32_e32 v215, v141, v141
	s_waitcnt vmcnt(3)
	v_pk_add_f32 v[130:131], v[130:131], v[112:113] op_sel_hi:[1,0] neg_lo:[0,1] neg_hi:[0,1]
	v_pk_add_f32 v[132:133], v[132:133], v[112:113] op_sel_hi:[1,0] neg_lo:[0,1] neg_hi:[0,1]
	v_pk_mul_f32 v[130:131], v[130:131], v[112:113] op_sel:[0,1] op_sel_hi:[1,1]
	v_pk_mul_f32 v[132:133], v[132:133], v[112:113] op_sel:[0,1] op_sel_hi:[1,1]
	v_pk_fma_f32 v[130:131], v[192:193], v[130:131], v[196:197]
	v_pk_fma_f32 v[132:133], v[194:195], v[132:133], v[198:199]
	v_pk_mul_f32 v[130:131], v[130:131], s[82:83] op_sel_hi:[1,0]
	v_pk_mul_f32 v[132:133], v[132:133], s[82:83] op_sel_hi:[1,0]
	v_pk_fma_f32 v[92:93], v[92:93], 0.5, v[130:131] op_sel_hi:[1,0,1]
	v_pk_fma_f32 v[94:95], v[94:95], 0.5, v[132:133] op_sel_hi:[1,0,1]
	global_load_dwordx4 v[130:133], v242, s[60:61] offset:64
	v_add_f32_e32 v214, v214, v92
	v_add_f32_e32 v214, v214, v93
	v_add_f32_e32 v214, v214, v94
	v_add_f32_e32 v214, v214, v95
	v_fmac_f32_e32 v215, v92, v92
	v_fmac_f32_e32 v215, v93, v93
	v_fmac_f32_e32 v215, v94, v94
	v_fmac_f32_e32 v215, v95, v95
	s_waitcnt vmcnt(3)
	v_pk_add_f32 v[134:135], v[134:135], v[200:201] op_sel_hi:[1,0] neg_lo:[0,1] neg_hi:[0,1]
	v_pk_add_f32 v[136:137], v[136:137], v[200:201] op_sel_hi:[1,0] neg_lo:[0,1] neg_hi:[0,1]
	v_pk_mul_f32 v[134:135], v[134:135], v[200:201] op_sel:[0,1] op_sel_hi:[1,1]
	v_pk_mul_f32 v[136:137], v[136:137], v[200:201] op_sel:[0,1] op_sel_hi:[1,1]
	v_pk_fma_f32 v[134:135], v[184:185], v[134:135], v[188:189]
	v_pk_fma_f32 v[136:137], v[186:187], v[136:137], v[190:191]
	v_pk_mul_f32 v[134:135], v[134:135], s[82:83] op_sel_hi:[1,0]
	v_pk_mul_f32 v[136:137], v[136:137], s[82:83] op_sel_hi:[1,0]
	v_pk_fma_f32 v[126:127], v[126:127], 0.5, v[134:135] op_sel_hi:[1,0,1]
	v_pk_fma_f32 v[128:129], v[128:129], 0.5, v[136:137] op_sel_hi:[1,0,1]
	global_load_dwordx4 v[134:137], v243, s[60:61]
	v_add_f32_e32 v216, v216, v126
	v_add_f32_e32 v216, v216, v127
	v_add_f32_e32 v216, v216, v128
	v_add_f32_e32 v216, v216, v129
	v_fmac_f32_e32 v217, v126, v126
	v_fmac_f32_e32 v217, v127, v127
	v_fmac_f32_e32 v217, v128, v128
	v_fmac_f32_e32 v217, v129, v129
	s_waitcnt vmcnt(3)
	v_pk_add_f32 v[180:181], v[180:181], v[200:201] op_sel_hi:[1,0] neg_lo:[0,1] neg_hi:[0,1]
	v_pk_add_f32 v[182:183], v[182:183], v[200:201] op_sel_hi:[1,0] neg_lo:[0,1] neg_hi:[0,1]
	v_pk_mul_f32 v[180:181], v[180:181], v[200:201] op_sel:[0,1] op_sel_hi:[1,1]
	v_pk_mul_f32 v[182:183], v[182:183], v[200:201] op_sel:[0,1] op_sel_hi:[1,1]
	v_pk_fma_f32 v[180:181], v[192:193], v[180:181], v[196:197]
	v_pk_fma_f32 v[182:183], v[194:195], v[182:183], v[198:199]
	v_pk_mul_f32 v[180:181], v[180:181], s[82:83] op_sel_hi:[1,0]
	v_pk_mul_f32 v[182:183], v[182:183], s[82:83] op_sel_hi:[1,0]
	v_pk_fma_f32 v[88:89], v[88:89], 0.5, v[180:181] op_sel_hi:[1,0,1]
	v_pk_fma_f32 v[90:91], v[90:91], 0.5, v[182:183] op_sel_hi:[1,0,1]
	global_load_dwordx4 v[180:183], v243, s[60:61] offset:64
	v_add_f32_e32 v216, v216, v88
	v_add_f32_e32 v216, v216, v89
	v_add_f32_e32 v216, v216, v90
	v_add_f32_e32 v216, v216, v91
	v_fmac_f32_e32 v217, v88, v88
	v_fmac_f32_e32 v217, v89, v89
	v_fmac_f32_e32 v217, v90, v90
	v_fmac_f32_e32 v217, v91, v91
	s_waitcnt vmcnt(3)
	v_pk_add_f32 v[108:109], v[108:109], v[202:203] op_sel_hi:[1,0] neg_lo:[0,1] neg_hi:[0,1]
	v_pk_add_f32 v[110:111], v[110:111], v[202:203] op_sel_hi:[1,0] neg_lo:[0,1] neg_hi:[0,1]
	v_pk_mul_f32 v[108:109], v[108:109], v[202:203] op_sel:[0,1] op_sel_hi:[1,1]
	v_pk_mul_f32 v[110:111], v[110:111], v[202:203] op_sel:[0,1] op_sel_hi:[1,1]
	v_pk_fma_f32 v[108:109], v[184:185], v[108:109], v[188:189]
	v_pk_fma_f32 v[110:111], v[186:187], v[110:111], v[190:191]
	v_pk_mul_f32 v[108:109], v[108:109], s[82:83] op_sel_hi:[1,0]
	v_pk_mul_f32 v[110:111], v[110:111], s[82:83] op_sel_hi:[1,0]
	v_pk_fma_f32 v[122:123], v[122:123], 0.5, v[108:109] op_sel_hi:[1,0,1]
	v_pk_fma_f32 v[124:125], v[124:125], 0.5, v[110:111] op_sel_hi:[1,0,1]
	global_load_dwordx4 v[108:111], v244, s[60:61]
	v_add_f32_e32 v218, v218, v122
	v_add_f32_e32 v218, v218, v123
	v_add_f32_e32 v218, v218, v124
	v_add_f32_e32 v218, v218, v125
	v_fmac_f32_e32 v219, v122, v122
	v_fmac_f32_e32 v219, v123, v123
	v_fmac_f32_e32 v219, v124, v124
	v_fmac_f32_e32 v219, v125, v125
	s_waitcnt vmcnt(3)
	v_pk_add_f32 v[130:131], v[130:131], v[202:203] op_sel_hi:[1,0] neg_lo:[0,1] neg_hi:[0,1]
	v_pk_add_f32 v[132:133], v[132:133], v[202:203] op_sel_hi:[1,0] neg_lo:[0,1] neg_hi:[0,1]
	v_pk_mul_f32 v[130:131], v[130:131], v[202:203] op_sel:[0,1] op_sel_hi:[1,1]
	v_pk_mul_f32 v[132:133], v[132:133], v[202:203] op_sel:[0,1] op_sel_hi:[1,1]
	v_pk_fma_f32 v[130:131], v[192:193], v[130:131], v[196:197]
	v_pk_fma_f32 v[132:133], v[194:195], v[132:133], v[198:199]
	v_pk_mul_f32 v[130:131], v[130:131], s[82:83] op_sel_hi:[1,0]
	v_pk_mul_f32 v[132:133], v[132:133], s[82:83] op_sel_hi:[1,0]
	v_pk_fma_f32 v[84:85], v[84:85], 0.5, v[130:131] op_sel_hi:[1,0,1]
	v_pk_fma_f32 v[86:87], v[86:87], 0.5, v[132:133] op_sel_hi:[1,0,1]
	global_load_dwordx4 v[130:133], v244, s[60:61] offset:64
	v_add_f32_e32 v218, v218, v84
	v_add_f32_e32 v218, v218, v85
	v_add_f32_e32 v218, v218, v86
	v_add_f32_e32 v218, v218, v87
	v_fmac_f32_e32 v219, v84, v84
	v_fmac_f32_e32 v219, v85, v85
	v_fmac_f32_e32 v219, v86, v86
	v_fmac_f32_e32 v219, v87, v87
	s_waitcnt vmcnt(3)
	v_pk_add_f32 v[134:135], v[134:135], v[204:205] op_sel_hi:[1,0] neg_lo:[0,1] neg_hi:[0,1]
	v_pk_add_f32 v[136:137], v[136:137], v[204:205] op_sel_hi:[1,0] neg_lo:[0,1] neg_hi:[0,1]
	v_pk_mul_f32 v[134:135], v[134:135], v[204:205] op_sel:[0,1] op_sel_hi:[1,1]
	v_pk_mul_f32 v[136:137], v[136:137], v[204:205] op_sel:[0,1] op_sel_hi:[1,1]
	v_pk_fma_f32 v[134:135], v[184:185], v[134:135], v[188:189]
	v_pk_fma_f32 v[136:137], v[186:187], v[136:137], v[190:191]
	v_pk_mul_f32 v[134:135], v[134:135], s[82:83] op_sel_hi:[1,0]
	v_pk_mul_f32 v[136:137], v[136:137], s[82:83] op_sel_hi:[1,0]
	v_pk_fma_f32 v[118:119], v[118:119], 0.5, v[134:135] op_sel_hi:[1,0,1]
	v_pk_fma_f32 v[120:121], v[120:121], 0.5, v[136:137] op_sel_hi:[1,0,1]
	global_load_dwordx4 v[134:137], v245, s[60:61]
	v_add_f32_e32 v220, v220, v118
	v_add_f32_e32 v220, v220, v119
	v_add_f32_e32 v220, v220, v120
	v_add_f32_e32 v220, v220, v121
	v_fmac_f32_e32 v221, v118, v118
	v_fmac_f32_e32 v221, v119, v119
	v_fmac_f32_e32 v221, v120, v120
	v_fmac_f32_e32 v221, v121, v121
	s_waitcnt vmcnt(3)
	v_pk_add_f32 v[180:181], v[180:181], v[204:205] op_sel_hi:[1,0] neg_lo:[0,1] neg_hi:[0,1]
	v_pk_add_f32 v[182:183], v[182:183], v[204:205] op_sel_hi:[1,0] neg_lo:[0,1] neg_hi:[0,1]
	v_pk_mul_f32 v[180:181], v[180:181], v[204:205] op_sel:[0,1] op_sel_hi:[1,1]
	v_pk_mul_f32 v[182:183], v[182:183], v[204:205] op_sel:[0,1] op_sel_hi:[1,1]
	v_pk_fma_f32 v[180:181], v[192:193], v[180:181], v[196:197]
	v_pk_fma_f32 v[182:183], v[194:195], v[182:183], v[198:199]
	v_pk_mul_f32 v[180:181], v[180:181], s[82:83] op_sel_hi:[1,0]
	v_pk_mul_f32 v[182:183], v[182:183], s[82:83] op_sel_hi:[1,0]
	v_pk_fma_f32 v[80:81], v[80:81], 0.5, v[180:181] op_sel_hi:[1,0,1]
	v_pk_fma_f32 v[82:83], v[82:83], 0.5, v[182:183] op_sel_hi:[1,0,1]
	global_load_dwordx4 v[180:183], v245, s[60:61] offset:64
	v_add_f32_e32 v220, v220, v80
	v_add_f32_e32 v220, v220, v81
	v_add_f32_e32 v220, v220, v82
	v_add_f32_e32 v220, v220, v83
	v_fmac_f32_e32 v221, v80, v80
	v_fmac_f32_e32 v221, v81, v81
	v_fmac_f32_e32 v221, v82, v82
	v_fmac_f32_e32 v221, v83, v83
	s_waitcnt vmcnt(3)
	v_pk_add_f32 v[108:109], v[108:109], v[206:207] op_sel_hi:[1,0] neg_lo:[0,1] neg_hi:[0,1]
	v_pk_add_f32 v[110:111], v[110:111], v[206:207] op_sel_hi:[1,0] neg_lo:[0,1] neg_hi:[0,1]
	v_pk_mul_f32 v[108:109], v[108:109], v[206:207] op_sel:[0,1] op_sel_hi:[1,1]
	v_pk_mul_f32 v[110:111], v[110:111], v[206:207] op_sel:[0,1] op_sel_hi:[1,1]
	v_pk_fma_f32 v[108:109], v[184:185], v[108:109], v[188:189]
	v_pk_fma_f32 v[110:111], v[186:187], v[110:111], v[190:191]
	v_pk_mul_f32 v[108:109], v[108:109], s[82:83] op_sel_hi:[1,0]
	v_pk_mul_f32 v[110:111], v[110:111], s[82:83] op_sel_hi:[1,0]
	v_pk_fma_f32 v[114:115], v[114:115], 0.5, v[108:109] op_sel_hi:[1,0,1]
	v_pk_fma_f32 v[116:117], v[116:117], 0.5, v[110:111] op_sel_hi:[1,0,1]
	global_load_dwordx4 v[108:111], v246, s[60:61]
	v_add_f32_e32 v232, v232, v114
	v_add_f32_e32 v232, v232, v115
	v_add_f32_e32 v232, v232, v116
	v_add_f32_e32 v232, v232, v117
	v_fmac_f32_e32 v233, v114, v114
	v_fmac_f32_e32 v233, v115, v115
	v_fmac_f32_e32 v233, v116, v116
	v_fmac_f32_e32 v233, v117, v117
	s_waitcnt vmcnt(3)
	v_pk_add_f32 v[130:131], v[130:131], v[206:207] op_sel_hi:[1,0] neg_lo:[0,1] neg_hi:[0,1]
	v_pk_add_f32 v[132:133], v[132:133], v[206:207] op_sel_hi:[1,0] neg_lo:[0,1] neg_hi:[0,1]
	v_pk_mul_f32 v[130:131], v[130:131], v[206:207] op_sel:[0,1] op_sel_hi:[1,1]
	v_pk_mul_f32 v[132:133], v[132:133], v[206:207] op_sel:[0,1] op_sel_hi:[1,1]
	v_pk_fma_f32 v[130:131], v[192:193], v[130:131], v[196:197]
	v_pk_fma_f32 v[132:133], v[194:195], v[132:133], v[198:199]
	v_pk_mul_f32 v[130:131], v[130:131], s[82:83] op_sel_hi:[1,0]
	v_pk_mul_f32 v[132:133], v[132:133], s[82:83] op_sel_hi:[1,0]
	v_pk_fma_f32 v[76:77], v[76:77], 0.5, v[130:131] op_sel_hi:[1,0,1]
	v_pk_fma_f32 v[78:79], v[78:79], 0.5, v[132:133] op_sel_hi:[1,0,1]
	global_load_dwordx4 v[130:133], v246, s[60:61] offset:64
	v_add_f32_e32 v232, v232, v76
	v_add_f32_e32 v232, v232, v77
	v_add_f32_e32 v232, v232, v78
	v_add_f32_e32 v232, v232, v79
	v_fmac_f32_e32 v233, v76, v76
	v_fmac_f32_e32 v233, v77, v77
	v_fmac_f32_e32 v233, v78, v78
	v_fmac_f32_e32 v233, v79, v79
	s_waitcnt vmcnt(3)
	v_pk_add_f32 v[134:135], v[134:135], v[208:209] op_sel_hi:[1,0] neg_lo:[0,1] neg_hi:[0,1]
	v_pk_add_f32 v[136:137], v[136:137], v[208:209] op_sel_hi:[1,0] neg_lo:[0,1] neg_hi:[0,1]
	v_pk_mul_f32 v[134:135], v[134:135], v[208:209] op_sel:[0,1] op_sel_hi:[1,1]
	v_pk_mul_f32 v[136:137], v[136:137], v[208:209] op_sel:[0,1] op_sel_hi:[1,1]
	v_pk_fma_f32 v[134:135], v[184:185], v[134:135], v[188:189]
	v_pk_fma_f32 v[136:137], v[186:187], v[136:137], v[190:191]
	v_pk_mul_f32 v[134:135], v[134:135], s[82:83] op_sel_hi:[1,0]
	v_pk_mul_f32 v[136:137], v[136:137], s[82:83] op_sel_hi:[1,0]
	v_pk_fma_f32 v[104:105], v[104:105], 0.5, v[134:135] op_sel_hi:[1,0,1]
	v_pk_fma_f32 v[106:107], v[106:107], 0.5, v[136:137] op_sel_hi:[1,0,1]
	global_load_dwordx4 v[134:137], v247, s[60:61]
	v_add_f32_e32 v234, v234, v104
	v_add_f32_e32 v234, v234, v105
	v_add_f32_e32 v234, v234, v106
	v_add_f32_e32 v234, v234, v107
	v_fmac_f32_e32 v235, v104, v104
	v_fmac_f32_e32 v235, v105, v105
	v_fmac_f32_e32 v235, v106, v106
	v_fmac_f32_e32 v235, v107, v107
	s_waitcnt vmcnt(3)
	v_pk_add_f32 v[180:181], v[180:181], v[208:209] op_sel_hi:[1,0] neg_lo:[0,1] neg_hi:[0,1]
	v_pk_add_f32 v[182:183], v[182:183], v[208:209] op_sel_hi:[1,0] neg_lo:[0,1] neg_hi:[0,1]
	v_pk_mul_f32 v[180:181], v[180:181], v[208:209] op_sel:[0,1] op_sel_hi:[1,1]
	v_pk_mul_f32 v[182:183], v[182:183], v[208:209] op_sel:[0,1] op_sel_hi:[1,1]
	v_pk_fma_f32 v[180:181], v[192:193], v[180:181], v[196:197]
	v_pk_fma_f32 v[182:183], v[194:195], v[182:183], v[198:199]
	v_pk_mul_f32 v[180:181], v[180:181], s[82:83] op_sel_hi:[1,0]
	v_pk_mul_f32 v[182:183], v[182:183], s[82:83] op_sel_hi:[1,0]
	v_pk_fma_f32 v[72:73], v[72:73], 0.5, v[180:181] op_sel_hi:[1,0,1]
	v_pk_fma_f32 v[74:75], v[74:75], 0.5, v[182:183] op_sel_hi:[1,0,1]
	global_load_dwordx4 v[180:183], v247, s[60:61] offset:64
	v_add_f32_e32 v234, v234, v72
	v_add_f32_e32 v234, v234, v73
	v_add_f32_e32 v234, v234, v74
	v_add_f32_e32 v234, v234, v75
	v_fmac_f32_e32 v235, v72, v72
	v_fmac_f32_e32 v235, v73, v73
	v_fmac_f32_e32 v235, v74, v74
	v_fmac_f32_e32 v235, v75, v75
	s_waitcnt vmcnt(3)
	v_pk_add_f32 v[108:109], v[108:109], v[210:211] op_sel_hi:[1,0] neg_lo:[0,1] neg_hi:[0,1]
	v_pk_add_f32 v[110:111], v[110:111], v[210:211] op_sel_hi:[1,0] neg_lo:[0,1] neg_hi:[0,1]
	v_pk_mul_f32 v[108:109], v[108:109], v[210:211] op_sel:[0,1] op_sel_hi:[1,1]
	v_pk_mul_f32 v[110:111], v[110:111], v[210:211] op_sel:[0,1] op_sel_hi:[1,1]
	v_pk_fma_f32 v[108:109], v[184:185], v[108:109], v[188:189]
	v_pk_fma_f32 v[110:111], v[186:187], v[110:111], v[190:191]
	v_pk_mul_f32 v[108:109], v[108:109], s[82:83] op_sel_hi:[1,0]
	v_pk_mul_f32 v[110:111], v[110:111], s[82:83] op_sel_hi:[1,0]
	v_pk_fma_f32 v[100:101], v[100:101], 0.5, v[108:109] op_sel_hi:[1,0,1]
	v_pk_fma_f32 v[102:103], v[102:103], 0.5, v[110:111] op_sel_hi:[1,0,1]
	global_load_dwordx4 v[108:111], v240, s[60:61] offset:512
	v_add_f32_e32 v236, v236, v100
	v_add_f32_e32 v236, v236, v101
	v_add_f32_e32 v236, v236, v102
	v_add_f32_e32 v236, v236, v103
	v_fmac_f32_e32 v237, v100, v100
	v_fmac_f32_e32 v237, v101, v101
	v_fmac_f32_e32 v237, v102, v102
	v_fmac_f32_e32 v237, v103, v103
	s_waitcnt vmcnt(3)
	v_pk_add_f32 v[130:131], v[130:131], v[210:211] op_sel_hi:[1,0] neg_lo:[0,1] neg_hi:[0,1]
	v_pk_add_f32 v[132:133], v[132:133], v[210:211] op_sel_hi:[1,0] neg_lo:[0,1] neg_hi:[0,1]
	v_pk_mul_f32 v[130:131], v[130:131], v[210:211] op_sel:[0,1] op_sel_hi:[1,1]
	v_pk_mul_f32 v[132:133], v[132:133], v[210:211] op_sel:[0,1] op_sel_hi:[1,1]
	v_pk_fma_f32 v[130:131], v[192:193], v[130:131], v[196:197]
	v_pk_fma_f32 v[132:133], v[194:195], v[132:133], v[198:199]
	v_pk_mul_f32 v[130:131], v[130:131], s[82:83] op_sel_hi:[1,0]
	v_pk_mul_f32 v[132:133], v[132:133], s[82:83] op_sel_hi:[1,0]
	v_pk_fma_f32 v[68:69], v[68:69], 0.5, v[130:131] op_sel_hi:[1,0,1]
	v_pk_fma_f32 v[70:71], v[70:71], 0.5, v[132:133] op_sel_hi:[1,0,1]
	global_load_dwordx4 v[130:133], v240, s[60:61] offset:576
	v_add_f32_e32 v236, v236, v68
	v_add_f32_e32 v236, v236, v69
	v_add_f32_e32 v236, v236, v70
	v_add_f32_e32 v236, v236, v71
	v_fmac_f32_e32 v237, v68, v68
	v_fmac_f32_e32 v237, v69, v69
	v_fmac_f32_e32 v237, v70, v70
	v_fmac_f32_e32 v237, v71, v71
	s_waitcnt vmcnt(3)
	v_pk_add_f32 v[134:135], v[134:135], v[212:213] op_sel_hi:[1,0] neg_lo:[0,1] neg_hi:[0,1]
	v_pk_add_f32 v[136:137], v[136:137], v[212:213] op_sel_hi:[1,0] neg_lo:[0,1] neg_hi:[0,1]
	v_pk_mul_f32 v[134:135], v[134:135], v[212:213] op_sel:[0,1] op_sel_hi:[1,1]
	v_pk_mul_f32 v[136:137], v[136:137], v[212:213] op_sel:[0,1] op_sel_hi:[1,1]
	v_pk_fma_f32 v[134:135], v[184:185], v[134:135], v[188:189]
	v_pk_fma_f32 v[136:137], v[186:187], v[136:137], v[190:191]
	v_pk_mul_f32 v[134:135], v[134:135], s[82:83] op_sel_hi:[1,0]
	v_pk_mul_f32 v[136:137], v[136:137], s[82:83] op_sel_hi:[1,0]
	v_pk_fma_f32 v[96:97], v[96:97], 0.5, v[134:135] op_sel_hi:[1,0,1]
	v_pk_fma_f32 v[98:99], v[98:99], 0.5, v[136:137] op_sel_hi:[1,0,1]
	global_load_dwordx4 v[134:137], v241, s[60:61] offset:512
	v_add_f32_e32 v238, v238, v96
	v_add_f32_e32 v238, v238, v97
	v_add_f32_e32 v238, v238, v98
	v_add_f32_e32 v238, v238, v99
	v_fmac_f32_e32 v239, v96, v96
	v_fmac_f32_e32 v239, v97, v97
	v_fmac_f32_e32 v239, v98, v98
	v_fmac_f32_e32 v239, v99, v99
	s_waitcnt vmcnt(3)
	v_pk_add_f32 v[180:181], v[180:181], v[212:213] op_sel_hi:[1,0] neg_lo:[0,1] neg_hi:[0,1]
	v_pk_add_f32 v[182:183], v[182:183], v[212:213] op_sel_hi:[1,0] neg_lo:[0,1] neg_hi:[0,1]
	v_pk_mul_f32 v[180:181], v[180:181], v[212:213] op_sel:[0,1] op_sel_hi:[1,1]
	v_pk_mul_f32 v[182:183], v[182:183], v[212:213] op_sel:[0,1] op_sel_hi:[1,1]
	v_pk_fma_f32 v[180:181], v[192:193], v[180:181], v[196:197]
	v_pk_fma_f32 v[182:183], v[194:195], v[182:183], v[198:199]
	v_pk_mul_f32 v[180:181], v[180:181], s[82:83] op_sel_hi:[1,0]
	v_pk_mul_f32 v[182:183], v[182:183], s[82:83] op_sel_hi:[1,0]
	v_pk_fma_f32 v[64:65], v[64:65], 0.5, v[180:181] op_sel_hi:[1,0,1]
	v_pk_fma_f32 v[66:67], v[66:67], 0.5, v[182:183] op_sel_hi:[1,0,1]
	global_load_dwordx4 v[180:183], v241, s[60:61] offset:576
	v_add_f32_e32 v238, v238, v64
	v_add_f32_e32 v238, v238, v65
	v_add_f32_e32 v238, v238, v66
	v_add_f32_e32 v238, v238, v67
	v_fmac_f32_e32 v239, v64, v64
	v_fmac_f32_e32 v239, v65, v65
	v_fmac_f32_e32 v239, v66, v66
	v_fmac_f32_e32 v239, v67, v67
	global_load_dwordx4 v[184:187], v249, s[48:49] offset:512
	global_load_dwordx4 v[188:191], v249, s[84:85] offset:512
	global_load_dwordx4 v[192:195], v249, s[48:49] offset:576
	global_load_dwordx4 v[196:199], v249, s[84:85] offset:576
	s_waitcnt vmcnt(0)
	v_pk_add_f32 v[108:109], v[108:109], v[112:113] op_sel_hi:[1,0] neg_lo:[0,1] neg_hi:[0,1]
	v_pk_add_f32 v[110:111], v[110:111], v[112:113] op_sel_hi:[1,0] neg_lo:[0,1] neg_hi:[0,1]
	v_pk_mul_f32 v[108:109], v[108:109], v[112:113] op_sel:[0,1] op_sel_hi:[1,1]
	v_pk_mul_f32 v[110:111], v[110:111], v[112:113] op_sel:[0,1] op_sel_hi:[1,1]
	v_pk_fma_f32 v[108:109], v[184:185], v[108:109], v[188:189]
	v_pk_fma_f32 v[110:111], v[186:187], v[110:111], v[190:191]
	v_pk_mul_f32 v[108:109], v[108:109], s[82:83] op_sel_hi:[1,0]
	v_pk_mul_f32 v[110:111], v[110:111], s[82:83] op_sel_hi:[1,0]
	v_pk_fma_f32 v[60:61], v[60:61], 0.5, v[108:109] op_sel_hi:[1,0,1]
	v_pk_fma_f32 v[62:63], v[62:63], 0.5, v[110:111] op_sel_hi:[1,0,1]
	global_load_dwordx4 v[108:111], v242, s[60:61] offset:512
	v_add_f32_e32 v214, v214, v60
	v_add_f32_e32 v214, v214, v61
	v_add_f32_e32 v214, v214, v62
	v_add_f32_e32 v214, v214, v63
	v_fmac_f32_e32 v215, v60, v60
	v_fmac_f32_e32 v215, v61, v61
	v_fmac_f32_e32 v215, v62, v62
	v_fmac_f32_e32 v215, v63, v63
	v_pk_add_f32 v[130:131], v[130:131], v[112:113] op_sel_hi:[1,0] neg_lo:[0,1] neg_hi:[0,1]
	v_pk_add_f32 v[132:133], v[132:133], v[112:113] op_sel_hi:[1,0] neg_lo:[0,1] neg_hi:[0,1]
	v_pk_mul_f32 v[130:131], v[130:131], v[112:113] op_sel:[0,1] op_sel_hi:[1,1]
	v_pk_mul_f32 v[132:133], v[132:133], v[112:113] op_sel:[0,1] op_sel_hi:[1,1]
	v_pk_fma_f32 v[130:131], v[192:193], v[130:131], v[196:197]
	v_pk_fma_f32 v[132:133], v[194:195], v[132:133], v[198:199]
	v_pk_mul_f32 v[130:131], v[130:131], s[82:83] op_sel_hi:[1,0]
	v_pk_mul_f32 v[132:133], v[132:133], s[82:83] op_sel_hi:[1,0]
	v_pk_fma_f32 v[28:29], v[28:29], 0.5, v[130:131] op_sel_hi:[1,0,1]
	v_pk_fma_f32 v[30:31], v[30:31], 0.5, v[132:133] op_sel_hi:[1,0,1]
	global_load_dwordx4 v[130:133], v242, s[60:61] offset:576
	v_add_f32_e32 v214, v214, v28
	v_add_f32_e32 v214, v214, v29
	v_add_f32_e32 v214, v214, v30
	v_add_f32_e32 v214, v214, v31
	v_fmac_f32_e32 v215, v28, v28
	v_fmac_f32_e32 v215, v29, v29
	v_fmac_f32_e32 v215, v30, v30
	v_fmac_f32_e32 v215, v31, v31
	v_pk_add_f32 v[134:135], v[134:135], v[200:201] op_sel_hi:[1,0] neg_lo:[0,1] neg_hi:[0,1]
	v_pk_add_f32 v[136:137], v[136:137], v[200:201] op_sel_hi:[1,0] neg_lo:[0,1] neg_hi:[0,1]
	v_pk_mul_f32 v[134:135], v[134:135], v[200:201] op_sel:[0,1] op_sel_hi:[1,1]
	v_pk_mul_f32 v[136:137], v[136:137], v[200:201] op_sel:[0,1] op_sel_hi:[1,1]
	v_pk_fma_f32 v[134:135], v[184:185], v[134:135], v[188:189]
	v_pk_fma_f32 v[136:137], v[186:187], v[136:137], v[190:191]
	v_pk_mul_f32 v[134:135], v[134:135], s[82:83] op_sel_hi:[1,0]
	v_pk_mul_f32 v[136:137], v[136:137], s[82:83] op_sel_hi:[1,0]
	v_pk_fma_f32 v[56:57], v[56:57], 0.5, v[134:135] op_sel_hi:[1,0,1]
	v_pk_fma_f32 v[58:59], v[58:59], 0.5, v[136:137] op_sel_hi:[1,0,1]
	global_load_dwordx4 v[134:137], v243, s[60:61] offset:512
	v_add_f32_e32 v216, v216, v56
	v_add_f32_e32 v216, v216, v57
	v_add_f32_e32 v216, v216, v58
	v_add_f32_e32 v216, v216, v59
	v_fmac_f32_e32 v217, v56, v56
	v_fmac_f32_e32 v217, v57, v57
	v_fmac_f32_e32 v217, v58, v58
	v_fmac_f32_e32 v217, v59, v59
	v_pk_add_f32 v[180:181], v[180:181], v[200:201] op_sel_hi:[1,0] neg_lo:[0,1] neg_hi:[0,1]
	v_pk_add_f32 v[182:183], v[182:183], v[200:201] op_sel_hi:[1,0] neg_lo:[0,1] neg_hi:[0,1]
	v_pk_mul_f32 v[180:181], v[180:181], v[200:201] op_sel:[0,1] op_sel_hi:[1,1]
	v_pk_mul_f32 v[182:183], v[182:183], v[200:201] op_sel:[0,1] op_sel_hi:[1,1]
	v_pk_fma_f32 v[180:181], v[192:193], v[180:181], v[196:197]
	v_pk_fma_f32 v[182:183], v[194:195], v[182:183], v[198:199]
	v_pk_mul_f32 v[180:181], v[180:181], s[82:83] op_sel_hi:[1,0]
	v_pk_mul_f32 v[182:183], v[182:183], s[82:83] op_sel_hi:[1,0]
	v_pk_fma_f32 v[24:25], v[24:25], 0.5, v[180:181] op_sel_hi:[1,0,1]
	v_pk_fma_f32 v[26:27], v[26:27], 0.5, v[182:183] op_sel_hi:[1,0,1]
	global_load_dwordx4 v[180:183], v243, s[60:61] offset:576
	v_add_f32_e32 v216, v216, v24
	v_add_f32_e32 v216, v216, v25
	v_add_f32_e32 v216, v216, v26
	v_add_f32_e32 v216, v216, v27
	v_fmac_f32_e32 v217, v24, v24
	v_fmac_f32_e32 v217, v25, v25
	v_fmac_f32_e32 v217, v26, v26
	v_fmac_f32_e32 v217, v27, v27
	s_waitcnt vmcnt(3)
	v_pk_add_f32 v[108:109], v[108:109], v[202:203] op_sel_hi:[1,0] neg_lo:[0,1] neg_hi:[0,1]
	v_pk_add_f32 v[110:111], v[110:111], v[202:203] op_sel_hi:[1,0] neg_lo:[0,1] neg_hi:[0,1]
	v_pk_mul_f32 v[108:109], v[108:109], v[202:203] op_sel:[0,1] op_sel_hi:[1,1]
	v_pk_mul_f32 v[110:111], v[110:111], v[202:203] op_sel:[0,1] op_sel_hi:[1,1]
	v_pk_fma_f32 v[108:109], v[184:185], v[108:109], v[188:189]
	v_pk_fma_f32 v[110:111], v[186:187], v[110:111], v[190:191]
	v_pk_mul_f32 v[108:109], v[108:109], s[82:83] op_sel_hi:[1,0]
	v_pk_mul_f32 v[110:111], v[110:111], s[82:83] op_sel_hi:[1,0]
	v_pk_fma_f32 v[52:53], v[52:53], 0.5, v[108:109] op_sel_hi:[1,0,1]
	v_pk_fma_f32 v[54:55], v[54:55], 0.5, v[110:111] op_sel_hi:[1,0,1]
	global_load_dwordx4 v[108:111], v244, s[60:61] offset:512
	v_add_f32_e32 v218, v218, v52
	v_add_f32_e32 v218, v218, v53
	v_add_f32_e32 v218, v218, v54
	v_add_f32_e32 v218, v218, v55
	v_fmac_f32_e32 v219, v52, v52
	v_fmac_f32_e32 v219, v53, v53
	v_fmac_f32_e32 v219, v54, v54
	v_fmac_f32_e32 v219, v55, v55
	s_waitcnt vmcnt(3)
	v_pk_add_f32 v[130:131], v[130:131], v[202:203] op_sel_hi:[1,0] neg_lo:[0,1] neg_hi:[0,1]
	v_pk_add_f32 v[132:133], v[132:133], v[202:203] op_sel_hi:[1,0] neg_lo:[0,1] neg_hi:[0,1]
	v_pk_mul_f32 v[130:131], v[130:131], v[202:203] op_sel:[0,1] op_sel_hi:[1,1]
	v_pk_mul_f32 v[132:133], v[132:133], v[202:203] op_sel:[0,1] op_sel_hi:[1,1]
	v_pk_fma_f32 v[130:131], v[192:193], v[130:131], v[196:197]
	v_pk_fma_f32 v[132:133], v[194:195], v[132:133], v[198:199]
	v_pk_mul_f32 v[130:131], v[130:131], s[82:83] op_sel_hi:[1,0]
	v_pk_mul_f32 v[132:133], v[132:133], s[82:83] op_sel_hi:[1,0]
	v_pk_fma_f32 v[20:21], v[20:21], 0.5, v[130:131] op_sel_hi:[1,0,1]
	v_pk_fma_f32 v[22:23], v[22:23], 0.5, v[132:133] op_sel_hi:[1,0,1]
	global_load_dwordx4 v[130:133], v244, s[60:61] offset:576
	v_add_f32_e32 v218, v218, v20
	v_add_f32_e32 v218, v218, v21
	v_add_f32_e32 v218, v218, v22
	v_add_f32_e32 v218, v218, v23
	v_fmac_f32_e32 v219, v20, v20
	v_fmac_f32_e32 v219, v21, v21
	v_fmac_f32_e32 v219, v22, v22
	v_fmac_f32_e32 v219, v23, v23
	s_waitcnt vmcnt(3)
	v_pk_add_f32 v[134:135], v[134:135], v[204:205] op_sel_hi:[1,0] neg_lo:[0,1] neg_hi:[0,1]
	v_pk_add_f32 v[136:137], v[136:137], v[204:205] op_sel_hi:[1,0] neg_lo:[0,1] neg_hi:[0,1]
	v_pk_mul_f32 v[134:135], v[134:135], v[204:205] op_sel:[0,1] op_sel_hi:[1,1]
	v_pk_mul_f32 v[136:137], v[136:137], v[204:205] op_sel:[0,1] op_sel_hi:[1,1]
	v_pk_fma_f32 v[134:135], v[184:185], v[134:135], v[188:189]
	v_pk_fma_f32 v[136:137], v[186:187], v[136:137], v[190:191]
	v_pk_mul_f32 v[134:135], v[134:135], s[82:83] op_sel_hi:[1,0]
	v_pk_mul_f32 v[136:137], v[136:137], s[82:83] op_sel_hi:[1,0]
	v_pk_fma_f32 v[48:49], v[48:49], 0.5, v[134:135] op_sel_hi:[1,0,1]
	v_pk_fma_f32 v[50:51], v[50:51], 0.5, v[136:137] op_sel_hi:[1,0,1]
	global_load_dwordx4 v[134:137], v245, s[60:61] offset:512
	v_add_f32_e32 v220, v220, v48
	v_add_f32_e32 v220, v220, v49
	v_add_f32_e32 v220, v220, v50
	v_add_f32_e32 v220, v220, v51
	v_fmac_f32_e32 v221, v48, v48
	v_fmac_f32_e32 v221, v49, v49
	v_fmac_f32_e32 v221, v50, v50
	v_fmac_f32_e32 v221, v51, v51
	s_waitcnt vmcnt(3)
	v_pk_add_f32 v[180:181], v[180:181], v[204:205] op_sel_hi:[1,0] neg_lo:[0,1] neg_hi:[0,1]
	v_pk_add_f32 v[182:183], v[182:183], v[204:205] op_sel_hi:[1,0] neg_lo:[0,1] neg_hi:[0,1]
	v_pk_mul_f32 v[180:181], v[180:181], v[204:205] op_sel:[0,1] op_sel_hi:[1,1]
	v_pk_mul_f32 v[182:183], v[182:183], v[204:205] op_sel:[0,1] op_sel_hi:[1,1]
	v_pk_fma_f32 v[180:181], v[192:193], v[180:181], v[196:197]
	v_pk_fma_f32 v[182:183], v[194:195], v[182:183], v[198:199]
	v_pk_mul_f32 v[180:181], v[180:181], s[82:83] op_sel_hi:[1,0]
	v_pk_mul_f32 v[182:183], v[182:183], s[82:83] op_sel_hi:[1,0]
	v_pk_fma_f32 v[16:17], v[16:17], 0.5, v[180:181] op_sel_hi:[1,0,1]
	v_pk_fma_f32 v[18:19], v[18:19], 0.5, v[182:183] op_sel_hi:[1,0,1]
	global_load_dwordx4 v[180:183], v245, s[60:61] offset:576
	v_add_f32_e32 v220, v220, v16
	v_add_f32_e32 v220, v220, v17
	v_add_f32_e32 v220, v220, v18
	v_add_f32_e32 v220, v220, v19
	v_fmac_f32_e32 v221, v16, v16
	v_fmac_f32_e32 v221, v17, v17
	v_fmac_f32_e32 v221, v18, v18
	v_fmac_f32_e32 v221, v19, v19
	s_waitcnt vmcnt(3)
	v_pk_add_f32 v[108:109], v[108:109], v[206:207] op_sel_hi:[1,0] neg_lo:[0,1] neg_hi:[0,1]
	v_pk_add_f32 v[110:111], v[110:111], v[206:207] op_sel_hi:[1,0] neg_lo:[0,1] neg_hi:[0,1]
	v_pk_mul_f32 v[108:109], v[108:109], v[206:207] op_sel:[0,1] op_sel_hi:[1,1]
	v_pk_mul_f32 v[110:111], v[110:111], v[206:207] op_sel:[0,1] op_sel_hi:[1,1]
	v_pk_fma_f32 v[108:109], v[184:185], v[108:109], v[188:189]
	v_pk_fma_f32 v[110:111], v[186:187], v[110:111], v[190:191]
	v_pk_mul_f32 v[108:109], v[108:109], s[82:83] op_sel_hi:[1,0]
	v_pk_mul_f32 v[110:111], v[110:111], s[82:83] op_sel_hi:[1,0]
	v_pk_fma_f32 v[44:45], v[44:45], 0.5, v[108:109] op_sel_hi:[1,0,1]
	v_pk_fma_f32 v[46:47], v[46:47], 0.5, v[110:111] op_sel_hi:[1,0,1]
	global_load_dwordx4 v[108:111], v246, s[60:61] offset:512
	v_add_f32_e32 v232, v232, v44
	v_add_f32_e32 v232, v232, v45
	v_add_f32_e32 v232, v232, v46
	v_add_f32_e32 v232, v232, v47
	v_fmac_f32_e32 v233, v44, v44
	v_fmac_f32_e32 v233, v45, v45
	v_fmac_f32_e32 v233, v46, v46
	v_fmac_f32_e32 v233, v47, v47
	s_waitcnt vmcnt(3)
	v_pk_add_f32 v[130:131], v[130:131], v[206:207] op_sel_hi:[1,0] neg_lo:[0,1] neg_hi:[0,1]
	v_pk_add_f32 v[132:133], v[132:133], v[206:207] op_sel_hi:[1,0] neg_lo:[0,1] neg_hi:[0,1]
	v_pk_mul_f32 v[130:131], v[130:131], v[206:207] op_sel:[0,1] op_sel_hi:[1,1]
	v_pk_mul_f32 v[132:133], v[132:133], v[206:207] op_sel:[0,1] op_sel_hi:[1,1]
	v_pk_fma_f32 v[130:131], v[192:193], v[130:131], v[196:197]
	v_pk_fma_f32 v[132:133], v[194:195], v[132:133], v[198:199]
	v_pk_mul_f32 v[130:131], v[130:131], s[82:83] op_sel_hi:[1,0]
	v_pk_mul_f32 v[132:133], v[132:133], s[82:83] op_sel_hi:[1,0]
	v_pk_fma_f32 v[12:13], v[12:13], 0.5, v[130:131] op_sel_hi:[1,0,1]
	v_pk_fma_f32 v[14:15], v[14:15], 0.5, v[132:133] op_sel_hi:[1,0,1]
	global_load_dwordx4 v[130:133], v246, s[60:61] offset:576
	v_add_f32_e32 v232, v232, v12
	v_add_f32_e32 v232, v232, v13
	v_add_f32_e32 v232, v232, v14
	v_add_f32_e32 v232, v232, v15
	v_fmac_f32_e32 v233, v12, v12
	v_fmac_f32_e32 v233, v13, v13
	v_fmac_f32_e32 v233, v14, v14
	v_fmac_f32_e32 v233, v15, v15
	s_waitcnt vmcnt(3)
	v_pk_add_f32 v[134:135], v[134:135], v[208:209] op_sel_hi:[1,0] neg_lo:[0,1] neg_hi:[0,1]
	v_pk_add_f32 v[136:137], v[136:137], v[208:209] op_sel_hi:[1,0] neg_lo:[0,1] neg_hi:[0,1]
	v_pk_mul_f32 v[134:135], v[134:135], v[208:209] op_sel:[0,1] op_sel_hi:[1,1]
	v_pk_mul_f32 v[136:137], v[136:137], v[208:209] op_sel:[0,1] op_sel_hi:[1,1]
	v_pk_fma_f32 v[134:135], v[184:185], v[134:135], v[188:189]
	v_pk_fma_f32 v[136:137], v[186:187], v[136:137], v[190:191]
	v_pk_mul_f32 v[134:135], v[134:135], s[82:83] op_sel_hi:[1,0]
	v_pk_mul_f32 v[136:137], v[136:137], s[82:83] op_sel_hi:[1,0]
	v_pk_fma_f32 v[40:41], v[40:41], 0.5, v[134:135] op_sel_hi:[1,0,1]
	v_pk_fma_f32 v[42:43], v[42:43], 0.5, v[136:137] op_sel_hi:[1,0,1]
	global_load_dwordx4 v[134:137], v247, s[60:61] offset:512
	v_add_f32_e32 v234, v234, v40
	v_add_f32_e32 v234, v234, v41
	v_add_f32_e32 v234, v234, v42
	v_add_f32_e32 v234, v234, v43
	v_fmac_f32_e32 v235, v40, v40
	v_fmac_f32_e32 v235, v41, v41
	v_fmac_f32_e32 v235, v42, v42
	v_fmac_f32_e32 v235, v43, v43
	s_waitcnt vmcnt(3)
	v_pk_add_f32 v[180:181], v[180:181], v[208:209] op_sel_hi:[1,0] neg_lo:[0,1] neg_hi:[0,1]
	v_pk_add_f32 v[182:183], v[182:183], v[208:209] op_sel_hi:[1,0] neg_lo:[0,1] neg_hi:[0,1]
	v_pk_mul_f32 v[180:181], v[180:181], v[208:209] op_sel:[0,1] op_sel_hi:[1,1]
	v_pk_mul_f32 v[182:183], v[182:183], v[208:209] op_sel:[0,1] op_sel_hi:[1,1]
	v_pk_fma_f32 v[180:181], v[192:193], v[180:181], v[196:197]
	v_pk_fma_f32 v[182:183], v[194:195], v[182:183], v[198:199]
	v_pk_mul_f32 v[180:181], v[180:181], s[82:83] op_sel_hi:[1,0]
	v_pk_mul_f32 v[182:183], v[182:183], s[82:83] op_sel_hi:[1,0]
	v_pk_fma_f32 v[8:9], v[8:9], 0.5, v[180:181] op_sel_hi:[1,0,1]
	v_pk_fma_f32 v[10:11], v[10:11], 0.5, v[182:183] op_sel_hi:[1,0,1]
	global_load_dwordx4 v[180:183], v247, s[60:61] offset:576
	v_add_f32_e32 v234, v234, v8
	v_add_f32_e32 v234, v234, v9
	v_add_f32_e32 v234, v234, v10
	v_add_f32_e32 v234, v234, v11
	v_fmac_f32_e32 v235, v8, v8
	v_fmac_f32_e32 v235, v9, v9
	v_fmac_f32_e32 v235, v10, v10
	v_fmac_f32_e32 v235, v11, v11
	s_waitcnt vmcnt(3)
	v_pk_add_f32 v[108:109], v[108:109], v[210:211] op_sel_hi:[1,0] neg_lo:[0,1] neg_hi:[0,1]
	v_pk_add_f32 v[110:111], v[110:111], v[210:211] op_sel_hi:[1,0] neg_lo:[0,1] neg_hi:[0,1]
	v_pk_mul_f32 v[108:109], v[108:109], v[210:211] op_sel:[0,1] op_sel_hi:[1,1]
	v_pk_mul_f32 v[110:111], v[110:111], v[210:211] op_sel:[0,1] op_sel_hi:[1,1]
	v_pk_fma_f32 v[108:109], v[184:185], v[108:109], v[188:189]
	v_pk_fma_f32 v[110:111], v[186:187], v[110:111], v[190:191]
	v_pk_mul_f32 v[108:109], v[108:109], s[82:83] op_sel_hi:[1,0]
	v_pk_mul_f32 v[110:111], v[110:111], s[82:83] op_sel_hi:[1,0]
	v_pk_fma_f32 v[36:37], v[36:37], 0.5, v[108:109] op_sel_hi:[1,0,1]
	v_pk_fma_f32 v[38:39], v[38:39], 0.5, v[110:111] op_sel_hi:[1,0,1]
	v_add_f32_e32 v236, v236, v36
	v_add_f32_e32 v236, v236, v37
	v_add_f32_e32 v236, v236, v38
	v_add_f32_e32 v236, v236, v39
	v_fmac_f32_e32 v237, v36, v36
	v_fmac_f32_e32 v237, v37, v37
	v_fmac_f32_e32 v237, v38, v38
	v_fmac_f32_e32 v237, v39, v39
	s_waitcnt vmcnt(2)
	v_pk_add_f32 v[130:131], v[130:131], v[210:211] op_sel_hi:[1,0] neg_lo:[0,1] neg_hi:[0,1]
	v_pk_add_f32 v[132:133], v[132:133], v[210:211] op_sel_hi:[1,0] neg_lo:[0,1] neg_hi:[0,1]
	v_pk_mul_f32 v[130:131], v[130:131], v[210:211] op_sel:[0,1] op_sel_hi:[1,1]
	v_pk_mul_f32 v[132:133], v[132:133], v[210:211] op_sel:[0,1] op_sel_hi:[1,1]
	v_pk_fma_f32 v[130:131], v[192:193], v[130:131], v[196:197]
	v_pk_fma_f32 v[132:133], v[194:195], v[132:133], v[198:199]
	v_pk_mul_f32 v[130:131], v[130:131], s[82:83] op_sel_hi:[1,0]
	v_pk_mul_f32 v[132:133], v[132:133], s[82:83] op_sel_hi:[1,0]
	v_pk_fma_f32 v[4:5], v[4:5], 0.5, v[130:131] op_sel_hi:[1,0,1]
	v_pk_fma_f32 v[6:7], v[6:7], 0.5, v[132:133] op_sel_hi:[1,0,1]
	v_add_f32_e32 v236, v236, v4
	v_add_f32_e32 v236, v236, v5
	v_add_f32_e32 v236, v236, v6
	v_add_f32_e32 v236, v236, v7
	v_fmac_f32_e32 v237, v4, v4
	v_fmac_f32_e32 v237, v5, v5
	v_fmac_f32_e32 v237, v6, v6
	v_fmac_f32_e32 v237, v7, v7
	s_waitcnt vmcnt(1)
	v_pk_add_f32 v[134:135], v[134:135], v[212:213] op_sel_hi:[1,0] neg_lo:[0,1] neg_hi:[0,1]
	v_pk_add_f32 v[136:137], v[136:137], v[212:213] op_sel_hi:[1,0] neg_lo:[0,1] neg_hi:[0,1]
	v_pk_mul_f32 v[134:135], v[134:135], v[212:213] op_sel:[0,1] op_sel_hi:[1,1]
	v_pk_mul_f32 v[136:137], v[136:137], v[212:213] op_sel:[0,1] op_sel_hi:[1,1]
	v_pk_fma_f32 v[134:135], v[184:185], v[134:135], v[188:189]
	v_pk_fma_f32 v[136:137], v[186:187], v[136:137], v[190:191]
	v_pk_mul_f32 v[134:135], v[134:135], s[82:83] op_sel_hi:[1,0]
	v_pk_mul_f32 v[136:137], v[136:137], s[82:83] op_sel_hi:[1,0]
	v_pk_fma_f32 v[32:33], v[32:33], 0.5, v[134:135] op_sel_hi:[1,0,1]
	v_pk_fma_f32 v[34:35], v[34:35], 0.5, v[136:137] op_sel_hi:[1,0,1]
	v_add_f32_e32 v238, v238, v32
	v_add_f32_e32 v238, v238, v33
	v_add_f32_e32 v238, v238, v34
	v_add_f32_e32 v238, v238, v35
	v_fmac_f32_e32 v239, v32, v32
	v_fmac_f32_e32 v239, v33, v33
	v_fmac_f32_e32 v239, v34, v34
	v_fmac_f32_e32 v239, v35, v35
	s_waitcnt vmcnt(0)
	v_pk_add_f32 v[180:181], v[180:181], v[212:213] op_sel_hi:[1,0] neg_lo:[0,1] neg_hi:[0,1]
	v_pk_add_f32 v[182:183], v[182:183], v[212:213] op_sel_hi:[1,0] neg_lo:[0,1] neg_hi:[0,1]
	v_pk_mul_f32 v[180:181], v[180:181], v[212:213] op_sel:[0,1] op_sel_hi:[1,1]
	v_pk_mul_f32 v[182:183], v[182:183], v[212:213] op_sel:[0,1] op_sel_hi:[1,1]
	v_pk_fma_f32 v[180:181], v[192:193], v[180:181], v[196:197]
	v_pk_fma_f32 v[182:183], v[194:195], v[182:183], v[198:199]
	v_pk_mul_f32 v[180:181], v[180:181], s[82:83] op_sel_hi:[1,0]
	v_pk_mul_f32 v[182:183], v[182:183], s[82:83] op_sel_hi:[1,0]
	v_pk_fma_f32 v[0:1], v[0:1], 0.5, v[180:181] op_sel_hi:[1,0,1]
	v_pk_fma_f32 v[2:3], v[2:3], 0.5, v[182:183] op_sel_hi:[1,0,1]
	v_add_f32_e32 v238, v238, v0
	v_add_f32_e32 v238, v238, v1
	v_add_f32_e32 v238, v238, v2
	v_add_f32_e32 v238, v238, v3
	v_fmac_f32_e32 v239, v0, v0
	v_fmac_f32_e32 v239, v1, v1
	v_fmac_f32_e32 v239, v2, v2
	v_fmac_f32_e32 v239, v3, v3
	ds_swizzle_b32 v108, v214 offset:swizzle(SWAP,16)
	ds_swizzle_b32 v109, v215 offset:swizzle(SWAP,16)
	ds_swizzle_b32 v110, v216 offset:swizzle(SWAP,16)
	ds_swizzle_b32 v111, v217 offset:swizzle(SWAP,16)
	ds_swizzle_b32 v130, v218 offset:swizzle(SWAP,16)
	ds_swizzle_b32 v131, v219 offset:swizzle(SWAP,16)
	ds_swizzle_b32 v132, v220 offset:swizzle(SWAP,16)
	ds_swizzle_b32 v133, v221 offset:swizzle(SWAP,16)
	ds_swizzle_b32 v134, v232 offset:swizzle(SWAP,16)
	ds_swizzle_b32 v135, v233 offset:swizzle(SWAP,16)
	ds_swizzle_b32 v136, v234 offset:swizzle(SWAP,16)
	ds_swizzle_b32 v137, v235 offset:swizzle(SWAP,16)
	ds_swizzle_b32 v180, v236 offset:swizzle(SWAP,16)
	ds_swizzle_b32 v181, v237 offset:swizzle(SWAP,16)
	ds_swizzle_b32 v182, v238 offset:swizzle(SWAP,16)
	ds_swizzle_b32 v183, v239 offset:swizzle(SWAP,16)
	s_waitcnt lgkmcnt(0)
	v_add_f32_e32 v214, v214, v108
	v_add_f32_e32 v215, v215, v109
	v_add_f32_e32 v216, v216, v110
	v_add_f32_e32 v217, v217, v111
	v_add_f32_e32 v218, v218, v130
	v_add_f32_e32 v219, v219, v131
	v_add_f32_e32 v220, v220, v132
	v_add_f32_e32 v221, v221, v133
	v_add_f32_e32 v232, v232, v134
	v_add_f32_e32 v233, v233, v135
	v_add_f32_e32 v234, v234, v136
	v_add_f32_e32 v235, v235, v137
	v_add_f32_e32 v236, v236, v180
	v_add_f32_e32 v237, v237, v181
	v_add_f32_e32 v238, v238, v182
	v_add_f32_e32 v239, v239, v183
	v_mov_b32_e32 v108, v214
	v_mov_b32_e32 v109, v215
	v_mov_b32_e32 v110, v216
	v_mov_b32_e32 v111, v217
	v_mov_b32_e32 v130, v218
	v_mov_b32_e32 v131, v219
	v_mov_b32_e32 v132, v220
	v_mov_b32_e32 v133, v221
	v_mov_b32_e32 v134, v232
	v_mov_b32_e32 v135, v233
	v_mov_b32_e32 v136, v234
	v_mov_b32_e32 v137, v235
	v_mov_b32_e32 v180, v236
	v_mov_b32_e32 v181, v237
	v_mov_b32_e32 v182, v238
	v_mov_b32_e32 v183, v239
	s_nop 1
	v_permlane32_swap_b32_e32 v108, v214
	v_permlane32_swap_b32_e32 v109, v215
	v_permlane32_swap_b32_e32 v110, v216
	v_permlane32_swap_b32_e32 v111, v217
	v_permlane32_swap_b32_e32 v130, v218
	v_permlane32_swap_b32_e32 v131, v219
	v_permlane32_swap_b32_e32 v132, v220
	v_permlane32_swap_b32_e32 v133, v221
	v_permlane32_swap_b32_e32 v134, v232
	v_permlane32_swap_b32_e32 v135, v233
	v_permlane32_swap_b32_e32 v136, v234
	v_permlane32_swap_b32_e32 v137, v235
	v_permlane32_swap_b32_e32 v180, v236
	v_permlane32_swap_b32_e32 v181, v237
	v_permlane32_swap_b32_e32 v182, v238
	v_permlane32_swap_b32_e32 v183, v239
	v_add_f32_e32 v214, v214, v108
	v_add_f32_e32 v215, v215, v109
	v_add_f32_e32 v216, v216, v110
	v_add_f32_e32 v217, v217, v111
	v_add_f32_e32 v218, v218, v130
	v_add_f32_e32 v219, v219, v131
	v_add_f32_e32 v220, v220, v132
	v_add_f32_e32 v221, v221, v133
	v_add_f32_e32 v232, v232, v134
	v_add_f32_e32 v233, v233, v135
	v_add_f32_e32 v234, v234, v136
	v_add_f32_e32 v235, v235, v137
	v_add_f32_e32 v236, v236, v180
	v_add_f32_e32 v237, v237, v181
	v_add_f32_e32 v238, v238, v182
	v_add_f32_e32 v239, v239, v183
	v_lshrrev_b32_e32 v108, 5, v159
	v_lshl_add_u32 v108, v108, 8, v158
	v_lshlrev_b32_e32 v108, 3, v108
	v_add_u32_e32 v108, 0x20000, v108
	ds_write_b64 v108, v[214:215]
	ds_write_b64 v108, v[216:217] offset:128
	ds_write_b64 v108, v[218:219] offset:256
	ds_write_b64 v108, v[220:221] offset:384
	ds_write_b64 v108, v[232:233] offset:1024
	ds_write_b64 v108, v[234:235] offset:1152
	ds_write_b64 v108, v[236:237] offset:1280
	ds_write_b64 v108, v[238:239] offset:1408
	s_waitcnt lgkmcnt(0)
	s_barrier
	v_readfirstlane_b32 s6, v222
	v_readlane_b32 s8, v252, 14
	v_readlane_b32 s9, v252, 15
	s_nop 3
	s_lshr_b32 s6, s6, 6
	s_lshl_b32 s7, s4, 13
	s_add_u32 s10, s8, 0x16740800
	s_addc_u32 s11, s9, 0
	s_add_u32 s10, s10, s7
	s_addc_u32 s11, s11, 0
	s_lshl_b32 s7, s4, 2
	s_add_u32 s12, s8, 0x1daca000
	s_addc_u32 s13, s9, 0
	s_add_u32 s12, s12, s7
	s_addc_u32 s13, s13, 0
	s_cmp_gt_u32 s6, 3
	s_cbranch_scc1 .LfeAf_1
	v_lshlrev_b32_e32 v110, 3, v222
	v_add_u32_e32 v183, 0x20000, v110
	ds_read_b64 v[130:131], v183
	ds_read_b64 v[132:133], v183 offset:2048
	ds_read_b64 v[134:135], v183 offset:4096
	ds_read_b64 v[136:137], v183 offset:6144
	s_waitcnt lgkmcnt(0)
	v_add_f32_e32 v130, v130, v132
	v_add_f32_e32 v131, v131, v133
	v_add_f32_e32 v134, v134, v136
	v_add_f32_e32 v135, v135, v137
	v_add_f32_e32 v130, v130, v134
	v_add_f32_e32 v131, v131, v135
	v_lshl_add_u32 v111, s5, 11, v110
	global_store_dwordx2 v111, v[130:131], s[10:11] sc1
